# attention inner loop hand-written: rotated pipeline (K frags prefetched across barrier, V frags during QK, global KV a full tile ahead), swizzled K tile, exp/cvt under MFMAs; plus G2 GEMM loops
# speedup vs baseline: 1.0547x; 1.0216x over previous
.LBB0_217:
	s_add_u32 s4, s76, s0
	s_addc_u32 s5, s77, s1
	global_load_dwordx4 v[6:9], v4, s[4:5] offset:16
	global_load_dwordx4 v[10:13], v4, s[4:5]
	s_add_u32 s4, s78, s0
	s_addc_u32 s5, s79, s1
	global_load_dwordx4 v[14:17], v4, s[4:5]
	global_load_dwordx4 v[18:21], v4, s[4:5] offset:16
	s_add_u32 s0, s0, 32
	s_addc_u32 s1, s1, 0
	s_cmpk_eq_i32 s0, 0x100
	s_waitcnt vmcnt(2)
	v_max3_f32 v2, v2, |v10|, |v11|
	v_max3_f32 v2, v2, |v12|, |v13|
	s_waitcnt vmcnt(1)
	v_max3_f32 v3, v3, |v14|, |v15|
	v_max3_f32 v3, v3, |v16|, |v17|
	v_max3_f32 v2, v2, |v6|, |v7|
	s_waitcnt vmcnt(0)
	v_max3_f32 v3, v3, |v18|, |v19|
	v_max3_f32 v2, v2, |v8|, |v9|
	v_max3_f32 v3, v3, |v20|, |v21|
	s_cbranch_scc0 .LBB0_217
	s_cmpk_gt_u32 s2, 0x107f
	s_cbranch_scc1 .LBB0_227
	v_bfe_u32 v4, v1, 4, 2
	v_mul_f32_e32 v2, 0x41000000, v2
	v_mov_b32_e32 v65, 0
	v_lshlrev_b32_e32 v5, 4, v1
	v_mul_f32_e32 v2, v3, v2
	s_waitcnt lgkmcnt(0)
	s_and_b32 s28, s2, 3
	v_lshlrev_b32_e32 v8, 4, v4
	v_mov_b32_e32 v9, v65
	s_and_b32 s3, s2, 4
	s_lshr_b32 s16, s33, 3
	s_lshr_b32 s17, s2, 3
	v_and_b32_e32 v6, 0x70, v5
	v_mul_f32_e32 v5, 0x3fb8aa3b, v2
	v_lshl_add_u64 v[2:3], s[86:87], 0, v[8:9]
	s_mov_b64 s[4:5], 0xc850000
	s_lshl_b32 s0, s28, 7
	v_lshl_add_u64 v[66:67], v[2:3], 0, s[4:5]
	s_add_u32 s4, s86, s0
	v_mov_b32_e32 v7, v65
	s_addc_u32 s5, s87, 0
	v_lshl_add_u64 v[10:11], s[4:5], 0, v[6:7]
	s_mov_b64 s[4:5], 0x14c50000
	v_lshlrev_b32_e32 v64, 3, v4
	v_lshl_add_u64 v[68:69], v[10:11], 0, s[4:5]
	v_lshl_add_u64 v[2:3], s[86:87], 0, v[6:7]
	s_mov_b64 s[4:5], 0x16d50000
	v_and_b32_e32 v14, 15, v1
	v_lshl_add_u64 v[70:71], v[2:3], 0, s[4:5]
	v_lshl_add_u64 v[12:13], s[86:87], 0, v[64:65]
	s_mov_b64 s[4:5], 0x18e50000
	v_lshrrev_b32_e32 v62, 3, v1
	v_lshl_add_u64 v[72:73], v[12:13], 0, s[4:5]
	v_mul_u32_u24_e32 v7, 0x90, v14
	s_mov_b64 s[4:5], 0x14c58000
	s_movk_i32 s38, 0x4200
	v_lshrrev_b32_e32 v15, 1, v1
	v_mul_u32_u24_e32 v1, 0x48, v62
	v_add3_u32 v87, 0, v7, v8
	v_lshl_add_u64 v[74:75], v[10:11], 0, s[4:5]
	v_mad_u64_u32 v[8:9], s[4:5], v62, s38, 0
	v_lshlrev_b32_e32 v1, 1, v1
	v_or_b32_e32 v8, v8, v6
	v_add3_u32 v1, 0, v6, v1
	v_lshl_add_u64 v[6:7], s[86:87], 0, v[8:9]
	s_mov_b64 s[4:5], 0x16d50080
	v_mul_f32_e32 v2, 0xbf800347, v5
	s_movk_i32 s0, 0x1e0
	v_lshl_add_u64 v[76:77], v[6:7], 0, s[4:5]
	s_mov_b32 s4, 0x3f803f80
	s_mov_b32 s1, 0
	v_mov_b32_e32 v63, v65
	v_mov_b32_e32 v3, v2
	v_mov_b32_e32 v4, v2
	v_mov_b32_e32 v5, v2
	s_lshl_b32 s29, s28, 8
	v_and_or_b32 v86, v15, s0, v14
	v_sub_u32_e32 v88, 0, v64
	v_mov_b32_e32 v89, 0x108000
	s_mov_b32 s5, s4
	s_mov_b32 s6, s4
	s_mov_b32 s7, s4
	s_mov_b64 s[8:9], 0x8000
	s_mov_b64 s[12:13], 0x80
	v_and_b32_e32 v220, 0x3ff, v0
	v_lshrrev_b32_e32 v221, 3, v220
	v_lshrrev_b32_e32 v139, 1, v221
	v_and_b32_e32 v139, 7, v139
	v_and_b32_e32 v138, 7, v220
	v_xor_b32_e32 v139, v139, v138
	v_lshlrev_b32_e32 v139, 4, v139
	v_lshl_add_u32 v216, v221, 7, v139
	v_and_b32_e32 v221, 15, v220
	v_lshrrev_b32_e32 v139, 1, v221
	v_bfe_u32 v138, v220, 4, 2
	v_xor_b32_e32 v139, v139, v138
	v_lshlrev_b32_e32 v139, 4, v139
	v_lshl_add_u32 v217, v221, 7, v139
	v_xor_b32_e32 v218, 64, v217
	v_mul_u32_u24_e32 v139, 0x90, v221
	v_lshl_add_u32 v139, v138, 3, v139
	v_add_u32_e32 v219, 0x4800, v139

.LBB0_224:
	s_lshl_b32 s0, s0, 3
	s_or_b32 s0, s0, s3
	s_lshr_b32 s42, s0, 2
	s_mul_i32 s46, s42, 0x2100
	s_lshl_b32 s42, s15, 8
	s_add_i32 s43, s46, s42
	s_lshl_b32 s14, s14, 6
	s_and_b32 s14, s14, 0xc0
	v_add_u32_e32 v64, s43, v86
	s_or_b32 s14, s14, s29
	s_or_b32 s0, s0, s28
	v_lshlrev_b64 v[80:81], 11, v[64:65]
	v_or_b32_e32 v64, 16, v64
	s_lshl_b32 s42, s14, 1
	s_lshl_b64 s[44:45], s[0:1], 6
	s_mov_b32 s43, s1
	v_lshlrev_b64 v[78:79], 11, v[64:65]
	v_or_b32_e32 v64, s46, v62
	v_lshl_add_u64 v[6:7], v[66:67], 0, s[42:43]
	v_lshlrev_b64 v[84:85], 9, v[64:65]
	v_lshl_add_u64 v[10:11], s[44:45], 0, v[62:63]
	v_lshl_add_u64 v[8:9], v[6:7], 0, v[80:81]
	v_lshl_add_u64 v[12:13], v[68:69], 0, v[84:85]
	v_mad_u64_u32 v[14:15], s[42:43], v10, s38, v[70:71]
	v_lshl_add_u64 v[6:7], v[6:7], 0, v[78:79]
	v_mad_u32_u24 v15, v11, s38, v15
	global_load_dwordx4 v[90:93], v[12:13], off
	global_load_dwordx4 v[94:97], v[14:15], off
	global_load_dwordx4 v[46:49], v[8:9], off
	global_load_dwordx4 v[42:45], v[8:9], off offset:64
	global_load_dwordx4 v[34:37], v[6:7], off
	global_load_dwordx4 v[30:33], v[6:7], off offset:64
	v_mov_b32_e32 v10, 0
	s_cmp_eq_u32 s15, 0
	v_mov_b32_e32 v11, v10
	v_mov_b32_e32 v12, v10
	v_mov_b32_e32 v13, v10
	v_mov_b32_e32 v14, v10
	v_mov_b32_e32 v15, v10
	v_mov_b32_e32 v16, v10
	v_mov_b32_e32 v17, v10
	v_mov_b32_e32 v26, v10
	v_mov_b32_e32 v27, v10
	v_mov_b32_e32 v28, v10
	v_mov_b32_e32 v29, v10
	v_mov_b32_e32 v6, v10
	v_mov_b32_e32 v7, v10
	v_mov_b32_e32 v8, v10
	v_mov_b32_e32 v9, v10
	v_mov_b32_e32 v18, v10
	v_mov_b32_e32 v19, v10
	v_mov_b32_e32 v20, v10
	v_mov_b32_e32 v21, v10
	v_mov_b32_e32 v22, v10
	v_mov_b32_e32 v23, v10
	v_mov_b32_e32 v24, v10
	v_mov_b32_e32 v25, v10
	v_mov_b32_e32 v38, v10
	v_mov_b32_e32 v39, v10
	v_mov_b32_e32 v40, v10
	v_mov_b32_e32 v41, v10
	v_mov_b32_e32 v50, v10
	v_mov_b32_e32 v51, v10
	v_mov_b32_e32 v52, v10
	v_mov_b32_e32 v53, v10
	v_mov_b32_e32 v54, v10
	v_mov_b32_e32 v55, v10
	v_mov_b32_e32 v56, v10
	v_mov_b32_e32 v57, v10
	v_mov_b32_e32 v58, v10
	v_mov_b32_e32 v59, v10
	v_mov_b32_e32 v60, v10
	v_mad_u64_u32 v[82:83], s[42:43], s0, v89, v[76:77]
	s_cselect_b32 s0, 3, 0x83
	v_lshl_add_u64 v[84:85], v[74:75], 0, v[84:85]
	v_mov_b32_e32 v61, v10
	s_barrier
	s_waitcnt vmcnt(5)
	ds_write_b128 v216, v[90:93]
	s_waitcnt vmcnt(4)
	ds_write_b128 v1, v[94:97] offset:18432
	s_waitcnt lgkmcnt(0)
	s_barrier
	global_load_dwordx4 v[204:207], v[84:85], off
	global_load_dwordx4 v[208:211], v[82:83], off
	v_lshl_add_u64 v[84:85], v[84:85], 0, s[8:9]
	v_lshl_add_u64 v[82:83], v[82:83], 0, s[12:13]
	v_mov_b32_e32 v220, v217
	v_mov_b32_e32 v221, v218
	v_xor_b32_e32 v139, 0x2000, v216
	v_mov_b64_e32 v[212:213], s[4:5]
	v_mov_b64_e32 v[214:215], s[6:7]
	ds_read_b128 v[140:143], v220
	ds_read_b128 v[144:147], v221
	ds_read_b128 v[148:151], v220 offset:2048
	ds_read_b128 v[152:155], v221 offset:2048
	ds_read_b128 v[156:159], v220 offset:4096
	ds_read_b128 v[160:163], v221 offset:4096
	ds_read_b128 v[164:167], v220 offset:6144
	ds_read_b128 v[168:171], v221 offset:6144
.Lav2_loop:
	s_and_b32 s15, s39, 1
	s_mul_i32 s42, s15, 0x2400
	v_add_u32_e32 v138, s42, v219
	s_xor_b32 s15, s15, 1
	s_mul_i32 s15, s15, 0x2400
	s_waitcnt vmcnt(2) lgkmcnt(0)
	v_mfma_f32_16x16x32_bf16 v[90:93], v[140:143], v[46:49], v[2:5]
	ds_read_b64 v[172:173], v138
	v_mfma_f32_16x16x32_bf16 v[106:109], v[140:143], v[34:37], v[2:5]
	ds_read_b64 v[174:175], v138 offset:32
	v_mfma_f32_16x16x32_bf16 v[90:93], v[144:147], v[42:45], v[90:93]
	ds_read_b64 v[180:181], v138 offset:2304
	v_mfma_f32_16x16x32_bf16 v[106:109], v[144:147], v[30:33], v[106:109]
	ds_read_b64 v[182:183], v138 offset:2336
	v_mfma_f32_16x16x32_bf16 v[94:97], v[148:151], v[46:49], v[2:5]
	ds_read_b64 v[188:189], v138 offset:4608
	v_mfma_f32_16x16x32_bf16 v[110:113], v[148:151], v[34:37], v[2:5]
	ds_read_b64 v[190:191], v138 offset:4640
	v_mfma_f32_16x16x32_bf16 v[94:97], v[152:155], v[42:45], v[94:97]
	ds_read_b64 v[196:197], v138 offset:6912
	v_mfma_f32_16x16x32_bf16 v[110:113], v[152:155], v[30:33], v[110:113]
	ds_read_b64 v[198:199], v138 offset:6944
	v_mfma_f32_16x16x32_bf16 v[98:101], v[156:159], v[46:49], v[2:5]
	v_exp_f32_e32 v90, v90
	v_exp_f32_e32 v91, v91
	v_mfma_f32_16x16x32_bf16 v[114:117], v[156:159], v[34:37], v[2:5]
	v_exp_f32_e32 v92, v92
	v_exp_f32_e32 v93, v93
	v_mfma_f32_16x16x32_bf16 v[98:101], v[160:163], v[42:45], v[98:101]
	v_exp_f32_e32 v94, v94
	v_exp_f32_e32 v95, v95
	v_mfma_f32_16x16x32_bf16 v[114:117], v[160:163], v[30:33], v[114:117]
	v_exp_f32_e32 v96, v96
	v_exp_f32_e32 v97, v97
	v_mfma_f32_16x16x32_bf16 v[102:105], v[164:167], v[46:49], v[2:5]
	v_exp_f32_e32 v106, v106
	v_exp_f32_e32 v107, v107
	v_mfma_f32_16x16x32_bf16 v[118:121], v[164:167], v[34:37], v[2:5]
	v_exp_f32_e32 v108, v108
	v_exp_f32_e32 v109, v109
	v_mfma_f32_16x16x32_bf16 v[102:105], v[168:171], v[42:45], v[102:105]
	v_exp_f32_e32 v110, v110
	v_exp_f32_e32 v111, v111
	v_mfma_f32_16x16x32_bf16 v[118:121], v[168:171], v[30:33], v[118:121]
	v_exp_f32_e32 v112, v112
	v_exp_f32_e32 v113, v113
	s_nop 0
	v_cvt_pk_bf16_f32 v90, v90, v91
	v_cvt_pk_bf16_f32 v91, v92, v93
	v_cvt_pk_bf16_f32 v92, v94, v95
	v_cvt_pk_bf16_f32 v93, v96, v97
	v_cvt_pk_bf16_f32 v106, v106, v107
	v_cvt_pk_bf16_f32 v107, v108, v109
	v_cvt_pk_bf16_f32 v108, v110, v111
	v_cvt_pk_bf16_f32 v109, v112, v113
	v_add_u32_e32 v64, s15, v1
	s_waitcnt vmcnt(1)
	ds_write_b128 v139, v[204:207]
	s_waitcnt vmcnt(0)
	ds_write_b128 v64, v[208:211] offset:18432
	s_waitcnt lgkmcnt(2)
	v_mfma_f32_16x16x32_bf16 v[58:61], v[212:215], v[90:93], v[58:61]
	ds_read_b64 v[176:177], v138 offset:64
	ds_read_b64 v[178:179], v138 offset:96
	ds_read_b64 v[184:185], v138 offset:2368
	v_mfma_f32_16x16x32_bf16 v[54:57], v[212:215], v[106:109], v[54:57]
	ds_read_b64 v[186:187], v138 offset:2400
	ds_read_b64 v[192:193], v138 offset:4672
	ds_read_b64 v[194:195], v138 offset:4704
	v_mfma_f32_16x16x32_bf16 v[50:53], v[172:175], v[90:93], v[50:53]
	ds_read_b64 v[200:201], v138 offset:6976
	ds_read_b64 v[202:203], v138 offset:7008
	v_exp_f32_e32 v98, v98
	v_mfma_f32_16x16x32_bf16 v[38:41], v[172:175], v[106:109], v[38:41]
	v_exp_f32_e32 v99, v99
	v_exp_f32_e32 v100, v100
	v_exp_f32_e32 v101, v101
	v_exp_f32_e32 v102, v102
	v_mfma_f32_16x16x32_bf16 v[22:25], v[180:183], v[90:93], v[22:25]
	v_exp_f32_e32 v103, v103
	v_exp_f32_e32 v104, v104
	v_exp_f32_e32 v105, v105
	v_mfma_f32_16x16x32_bf16 v[18:21], v[180:183], v[106:109], v[18:21]
	v_exp_f32_e32 v114, v114
	v_exp_f32_e32 v115, v115
	v_exp_f32_e32 v116, v116
	v_mfma_f32_16x16x32_bf16 v[6:9], v[188:191], v[90:93], v[6:9]
	v_exp_f32_e32 v117, v117
	v_exp_f32_e32 v118, v118
	v_exp_f32_e32 v119, v119
	v_exp_f32_e32 v120, v120
	v_mfma_f32_16x16x32_bf16 v[26:29], v[188:191], v[106:109], v[26:29]
	v_exp_f32_e32 v121, v121
	s_nop 0
	v_cvt_pk_bf16_f32 v98, v98, v99
	v_mfma_f32_16x16x32_bf16 v[14:17], v[196:199], v[90:93], v[14:17]
	v_cvt_pk_bf16_f32 v99, v100, v101
	v_cvt_pk_bf16_f32 v100, v102, v103
	v_cvt_pk_bf16_f32 v101, v104, v105
	v_mfma_f32_16x16x32_bf16 v[10:13], v[196:199], v[106:109], v[10:13]
	v_cvt_pk_bf16_f32 v114, v114, v115
	v_cvt_pk_bf16_f32 v115, v116, v117
	v_cvt_pk_bf16_f32 v116, v118, v119
	v_cvt_pk_bf16_f32 v117, v120, v121
	s_waitcnt lgkmcnt(0)
	s_barrier
	s_add_i32 s39, s39, 1
	s_cmp_eq_u32 s0, s39
	s_cbranch_scc1 .Lav2_tail
	v_xor_b32_e32 v220, 0x2000, v220
	v_xor_b32_e32 v221, 0x2000, v221
	v_xor_b32_e32 v139, 0x2000, v139
	ds_read_b128 v[140:143], v220
	ds_read_b128 v[144:147], v221
	ds_read_b128 v[148:151], v220 offset:2048
	ds_read_b128 v[152:155], v221 offset:2048
	ds_read_b128 v[156:159], v220 offset:4096
	ds_read_b128 v[160:163], v221 offset:4096
	ds_read_b128 v[164:167], v220 offset:6144
	ds_read_b128 v[168:171], v221 offset:6144
	v_mfma_f32_16x16x32_bf16 v[58:61], v[212:215], v[98:101], v[58:61]
	v_mfma_f32_16x16x32_bf16 v[54:57], v[212:215], v[114:117], v[54:57]
	v_mfma_f32_16x16x32_bf16 v[50:53], v[176:179], v[98:101], v[50:53]
	global_load_dwordx4 v[204:207], v[84:85], off
	v_mfma_f32_16x16x32_bf16 v[38:41], v[176:179], v[114:117], v[38:41]
	v_mfma_f32_16x16x32_bf16 v[22:25], v[184:187], v[98:101], v[22:25]
	global_load_dwordx4 v[208:211], v[82:83], off
	v_mfma_f32_16x16x32_bf16 v[18:21], v[184:187], v[114:117], v[18:21]
	v_mfma_f32_16x16x32_bf16 v[6:9], v[192:195], v[98:101], v[6:9]
	v_mfma_f32_16x16x32_bf16 v[26:29], v[192:195], v[114:117], v[26:29]
	v_lshl_add_u64 v[84:85], v[84:85], 0, s[8:9]
	v_mfma_f32_16x16x32_bf16 v[14:17], v[200:203], v[98:101], v[14:17]
	v_mfma_f32_16x16x32_bf16 v[10:13], v[200:203], v[114:117], v[10:13]
	v_lshl_add_u64 v[82:83], v[82:83], 0, s[12:13]
	s_branch .Lav2_loop
.Lav2_tail:
	v_mfma_f32_16x16x32_bf16 v[58:61], v[212:215], v[98:101], v[58:61]
	v_mfma_f32_16x16x32_bf16 v[54:57], v[212:215], v[114:117], v[54:57]
	v_mfma_f32_16x16x32_bf16 v[50:53], v[176:179], v[98:101], v[50:53]
	v_mfma_f32_16x16x32_bf16 v[38:41], v[176:179], v[114:117], v[38:41]
	v_mfma_f32_16x16x32_bf16 v[22:25], v[184:187], v[98:101], v[22:25]
	v_mfma_f32_16x16x32_bf16 v[18:21], v[184:187], v[114:117], v[18:21]
	v_mfma_f32_16x16x32_bf16 v[6:9], v[192:195], v[98:101], v[6:9]
	v_mfma_f32_16x16x32_bf16 v[26:29], v[192:195], v[114:117], v[26:29]
	v_mfma_f32_16x16x32_bf16 v[14:17], v[200:203], v[98:101], v[14:17]
	v_mfma_f32_16x16x32_bf16 v[10:13], v[200:203], v[114:117], v[10:13]
	s_bitcmp1_b32 s0, 0
	s_cselect_b32 s0, 0x2400, 0
	v_add_u32_e32 v64, s0, v87
	s_min_u32 s98, s0, 0x2000
	v_add_u32_e32 v220, s98, v217
	v_xor_b32_e32 v221, 64, v220
	ds_read_b128 v[82:85], v220
	ds_read_b128 v[90:93], v221
	ds_read_b128 v[98:101], v220 offset:2048
	ds_read_b128 v[102:105], v221 offset:2048
	ds_read_b128 v[110:113], v220 offset:4096
	ds_read_b128 v[114:117], v221 offset:4096
	ds_read_b128 v[122:125], v220 offset:6144
	ds_read_b128 v[126:129], v221 offset:6144
	s_waitcnt lgkmcnt(7)
	v_mfma_f32_16x16x32_bf16 v[94:97], v[82:85], v[46:49], v[2:5]
	s_lshl_b32 s0, s14, 1
	s_add_i32 s17, s17, s16
	s_cmpk_gt_u32 s17, 0x20f
	s_waitcnt lgkmcnt(5)
	v_mfma_f32_16x16x32_bf16 v[106:109], v[98:101], v[46:49], v[2:5]
	s_waitcnt lgkmcnt(3)
	v_mfma_f32_16x16x32_bf16 v[118:121], v[110:113], v[46:49], v[2:5]
	v_mfma_f32_16x16x32_bf16 v[94:97], v[90:93], v[42:45], v[94:97]
	s_waitcnt lgkmcnt(1)
	v_mfma_f32_16x16x32_bf16 v[46:49], v[122:125], v[46:49], v[2:5]
	v_mfma_f32_16x16x32_bf16 v[106:109], v[102:105], v[42:45], v[106:109]
	s_nop 4
	v_exp_f32_e32 v130, v94
	v_exp_f32_e32 v131, v95
	v_exp_f32_e32 v132, v96
	v_exp_f32_e32 v133, v97
	v_mfma_f32_16x16x32_bf16 v[94:97], v[114:117], v[42:45], v[118:121]
	v_exp_f32_e32 v106, v106
	v_exp_f32_e32 v107, v107
	v_exp_f32_e32 v108, v108
	s_waitcnt lgkmcnt(0)
	v_mfma_f32_16x16x32_bf16 v[42:45], v[126:129], v[42:45], v[46:49]
	v_exp_f32_e32 v109, v109
	s_nop 1
	v_exp_f32_e32 v94, v94
	v_exp_f32_e32 v95, v95
	v_mfma_f32_16x16x32_bf16 v[46:49], v[82:85], v[34:37], v[2:5]
	v_exp_f32_e32 v96, v96
	v_exp_f32_e32 v97, v97
	v_cvt_pk_bf16_f32 v82, v94, v95
	v_mfma_f32_16x16x32_bf16 v[46:49], v[90:93], v[30:33], v[46:49]
	v_exp_f32_e32 v118, v42
	v_cvt_pk_bf16_f32 v83, v96, v97
	v_exp_f32_e32 v119, v43
	v_mfma_f32_16x16x32_bf16 v[90:93], v[98:101], v[34:37], v[2:5]
	v_exp_f32_e32 v120, v44
	s_nop 2
	v_exp_f32_e32 v98, v46
	v_exp_f32_e32 v99, v47
	v_mfma_f32_16x16x32_bf16 v[90:93], v[102:105], v[30:33], v[90:93]
	v_exp_f32_e32 v100, v48
	v_exp_f32_e32 v101, v49
	v_exp_f32_e32 v85, v45
	v_mfma_f32_16x16x32_bf16 v[94:97], v[110:113], v[34:37], v[2:5]
	v_cvt_pk_bf16_f32 v42, v130, v131
	s_nop 2
	v_exp_f32_e32 v102, v90
	v_exp_f32_e32 v103, v91
	v_mfma_f32_16x16x32_bf16 v[34:37], v[122:125], v[34:37], v[2:5]
	v_cvt_pk_bf16_f32 v43, v132, v133
	v_cvt_pk_bf16_f32 v44, v106, v107
	v_cvt_pk_bf16_f32 v45, v108, v109
	v_mfma_f32_16x16x32_bf16 v[46:49], v[114:117], v[30:33], v[94:97]
	v_cvt_pk_bf16_f32 v84, v118, v119
	v_cvt_pk_bf16_f32 v85, v120, v85
	s_nop 0
	v_exp_f32_e32 v94, v92
	v_exp_f32_e32 v95, v93
	v_mov_b64_e32 v[92:93], s[6:7]
	v_mov_b64_e32 v[90:91], s[4:5]
	v_mfma_f32_16x16x32_bf16 v[30:33], v[126:129], v[30:33], v[34:37]
	v_exp_f32_e32 v96, v46
	v_exp_f32_e32 v97, v47
	v_exp_f32_e32 v104, v48
	v_exp_f32_e32 v105, v49
	v_cvt_pk_bf16_f32 v34, v98, v99
	s_nop 2
	v_exp_f32_e32 v106, v30
	v_exp_f32_e32 v107, v31
	v_mfma_f32_16x16x32_bf16 v[46:49], v[90:93], v[42:45], v[58:61]
	v_cvt_pk_bf16_f32 v35, v100, v101
	v_cvt_pk_bf16_f32 v36, v102, v103
	v_cvt_pk_bf16_f32 v37, v94, v95
	v_exp_f32_e32 v58, v32
	v_exp_f32_e32 v33, v33
	v_mfma_f32_16x16x32_bf16 v[54:57], v[90:93], v[34:37], v[54:57]
	v_cvt_pk_bf16_f32 v30, v96, v97
	v_cvt_pk_bf16_f32 v31, v104, v105
	v_cvt_pk_bf16_f32 v32, v106, v107
	v_mfma_f32_16x16x32_bf16 v[46:49], v[90:93], v[82:85], v[46:49]
	v_cvt_pk_bf16_f32 v33, v58, v33
	s_nop 1
	v_mfma_f32_16x16x32_bf16 v[54:57], v[90:93], v[30:33], v[54:57]
	s_nop 3
	v_add_u32_e32 v47, v64, v88
	s_nop 2
	v_add_u32_e32 v55, 0x4800, v47
	ds_read2_b64 v[56:59], v55 offset1:4
	ds_read2_b64 v[90:93], v55 offset0:8 offset1:12
	s_waitcnt lgkmcnt(1)
	v_mfma_f32_16x16x32_bf16 v[48:51], v[56:59], v[42:45], v[50:53]
	s_nop 2
	v_add_u32_e32 v52, 0x5000, v47
	v_mfma_f32_16x16x32_bf16 v[38:41], v[56:59], v[34:37], v[38:41]
	ds_read2_b64 v[56:59], v52 offset0:32 offset1:36
	ds_read2_b64 v[94:97], v52 offset0:40 offset1:44
	v_add_u32_e32 v52, 0x5800, v47
	v_add_u32_e32 v47, 0x6000, v47
	s_waitcnt lgkmcnt(2)
	v_mfma_f32_16x16x32_bf16 v[48:51], v[90:93], v[82:85], v[48:51]
	ds_read2_b64 v[98:101], v52 offset0:64 offset1:68
	ds_read2_b64 v[102:105], v52 offset0:72 offset1:76
	v_lshl_add_u64 v[52:53], v[72:73], 0, s[0:1]
	v_mfma_f32_16x16x32_bf16 v[38:41], v[90:93], v[30:33], v[38:41]
	ds_read2_b64 v[90:93], v47 offset0:96 offset1:100
	ds_read2_b64 v[106:109], v47 offset0:104 offset1:108
	v_div_scale_f32 v47, s[42:43], v46, v46, 1.0
	v_rcp_f32_e32 v55, v47
	s_waitcnt lgkmcnt(5)
	v_mfma_f32_16x16x32_bf16 v[22:25], v[56:59], v[42:45], v[22:25]
	s_waitcnt lgkmcnt(0)
	s_barrier
	v_mfma_f32_16x16x32_bf16 v[18:21], v[56:59], v[34:37], v[18:21]
	v_fma_f32 v56, -v47, v55, 1.0
	v_fmac_f32_e32 v55, v56, v55
	v_div_scale_f32 v56, vcc, 1.0, v46, 1.0
	v_mfma_f32_16x16x32_bf16 v[6:9], v[98:101], v[42:45], v[6:9]
	v_mul_f32_e32 v57, v56, v55
	v_fma_f32 v58, -v47, v57, v56
	v_fmac_f32_e32 v57, v58, v55
	v_mfma_f32_16x16x32_bf16 v[14:17], v[90:93], v[42:45], v[14:17]
	v_fma_f32 v47, -v47, v57, v56
	v_div_fmas_f32 v47, v47, v55, v57
	v_div_fixup_f32 v46, v47, v46, 1.0
	v_mfma_f32_16x16x32_bf16 v[22:25], v[94:97], v[82:85], v[22:25]
	v_lshl_add_u64 v[56:57], v[52:53], 0, v[80:81]
	v_pk_mul_f32 v[50:51], v[46:47], v[50:51] op_sel_hi:[0,1]
	v_pk_mul_f32 v[48:49], v[46:47], v[48:49] op_sel_hi:[0,1]
	v_mfma_f32_16x16x32_bf16 v[6:9], v[102:105], v[82:85], v[6:9]
	v_cvt_pk_bf16_f32 v48, v48, v49
	s_nop 2
	v_pk_mul_f32 v[24:25], v[46:47], v[24:25] op_sel_hi:[0,1]
	v_pk_mul_f32 v[22:23], v[46:47], v[22:23] op_sel_hi:[0,1]
	v_mfma_f32_16x16x32_bf16 v[10:13], v[90:93], v[34:37], v[10:13]
	v_cvt_pk_bf16_f32 v22, v22, v23
	v_cvt_pk_bf16_f32 v23, v24, v25
	v_pk_mul_f32 v[8:9], v[46:47], v[8:9] op_sel_hi:[0,1]
	v_mfma_f32_16x16x32_bf16 v[14:17], v[106:109], v[82:85], v[14:17]
	v_mul_f32_e64 v6, v46, v6
	v_mul_f32_e64 v7, v46, v7
	global_store_dwordx2 v[56:57], v[22:23], off offset:32
	v_cvt_pk_bf16_f32 v22, v6, v7
	v_cvt_pk_bf16_f32 v23, v8, v9
	v_mfma_f32_16x16x32_bf16 v[6:9], v[106:109], v[30:33], v[10:13]
	v_cvt_pk_bf16_f32 v49, v50, v51
	global_store_dwordx2 v[56:57], v[48:49], off
	global_store_dwordx2 v[56:57], v[22:23], off offset:64
	v_pk_mul_f32 v[12:13], v[46:47], v[14:15] op_sel_hi:[0,1]
	v_div_scale_f32 v14, s[14:15], v54, v54, 1.0
	v_rcp_f32_e32 v15, v14
	v_pk_mul_f32 v[10:11], v[46:47], v[16:17] op_sel_hi:[0,1]
	v_cvt_pk_bf16_f32 v12, v12, v13
	v_cvt_pk_bf16_f32 v13, v10, v11
	v_fma_f32 v10, -v14, v15, 1.0
	v_fmac_f32_e32 v15, v10, v15
	v_div_scale_f32 v10, vcc, 1.0, v54, 1.0
	v_mul_f32_e32 v11, v10, v15
	global_store_dwordx2 v[56:57], v[12:13], off offset:96
	v_fma_f32 v12, -v14, v11, v10
	v_mfma_f32_16x16x32_bf16 v[26:29], v[98:101], v[34:37], v[26:29]
	v_fmac_f32_e32 v11, v12, v15
	v_fma_f32 v10, -v14, v11, v10
	v_div_fmas_f32 v10, v10, v15, v11
	v_mfma_f32_16x16x32_bf16 v[18:21], v[94:97], v[30:33], v[18:21]
	v_div_fixup_f32 v10, v10, v54, 1.0
	v_pk_mul_f32 v[14:15], v[10:11], v[40:41] op_sel_hi:[0,1]
	v_pk_mul_f32 v[16:17], v[10:11], v[38:39] op_sel_hi:[0,1]
	v_mfma_f32_16x16x32_bf16 v[26:29], v[102:105], v[30:33], v[26:29]
	v_lshl_add_u64 v[12:13], v[52:53], 0, v[78:79]
	v_cvt_pk_bf16_f32 v16, v16, v17
	v_cvt_pk_bf16_f32 v17, v14, v15
	global_store_dwordx2 v[12:13], v[16:17], off
	v_pk_mul_f32 v[14:15], v[10:11], v[20:21] op_sel_hi:[0,1]
	v_pk_mul_f32 v[16:17], v[10:11], v[18:19] op_sel_hi:[0,1]
	v_cvt_pk_bf16_f32 v16, v16, v17
	v_cvt_pk_bf16_f32 v17, v14, v15
	global_store_dwordx2 v[12:13], v[16:17], off offset:32
	v_pk_mul_f32 v[14:15], v[10:11], v[28:29] op_sel_hi:[0,1]
	v_pk_mul_f32 v[16:17], v[10:11], v[26:27] op_sel_hi:[0,1]
	v_pk_mul_f32 v[8:9], v[10:11], v[8:9] op_sel_hi:[0,1]
	v_pk_mul_f32 v[6:7], v[10:11], v[6:7] op_sel_hi:[0,1]
	v_cvt_pk_bf16_f32 v16, v16, v17
	v_cvt_pk_bf16_f32 v17, v14, v15
	v_cvt_pk_bf16_f32 v6, v6, v7
	v_cvt_pk_bf16_f32 v7, v8, v9
	global_store_dwordx2 v[12:13], v[16:17], off offset:64
	global_store_dwordx2 v[12:13], v[6:7], off offset:96
	s_cbranch_scc0 .LBB0_220

	.amdhsa_kernel _Z10fwd_kernel2Pm
		.amdhsa_group_segment_fixed_size 0
		.amdhsa_private_segment_fixed_size 0
		.amdhsa_kernarg_size 536
		.amdhsa_user_sgpr_count 2
		.amdhsa_user_sgpr_dispatch_ptr 0
		.amdhsa_user_sgpr_queue_ptr 0
		.amdhsa_user_sgpr_kernarg_segment_ptr 1
		.amdhsa_user_sgpr_dispatch_id 0
		.amdhsa_user_sgpr_kernarg_preload_length 0
		.amdhsa_user_sgpr_kernarg_preload_offset 0
		.amdhsa_user_sgpr_private_segment_size 0
		.amdhsa_uses_dynamic_stack 0
		.amdhsa_enable_private_segment 0
		.amdhsa_system_sgpr_workgroup_id_x 1
		.amdhsa_system_sgpr_workgroup_id_y 0
		.amdhsa_system_sgpr_workgroup_id_z 0
		.amdhsa_system_sgpr_workgroup_info 0
		.amdhsa_system_vgpr_workitem_id 2
		.amdhsa_next_free_vgpr 256
		.amdhsa_next_free_sgpr 102
		.amdhsa_accum_offset 256
		.amdhsa_reserve_vcc 1
		.amdhsa_float_round_mode_32 0
		.amdhsa_float_round_mode_16_64 0
		.amdhsa_float_denorm_mode_32 3
		.amdhsa_float_denorm_mode_16_64 3
		.amdhsa_dx10_clamp 1
		.amdhsa_ieee_mode 1
		.amdhsa_fp16_overflow 0
		.amdhsa_tg_split 0
		.amdhsa_exception_fp_ieee_invalid_op 0
		.amdhsa_exception_fp_denorm_src 0
		.amdhsa_exception_fp_ieee_div_zero 0
		.amdhsa_exception_fp_ieee_overflow 0
		.amdhsa_exception_fp_ieee_underflow 0
		.amdhsa_exception_fp_ieee_inexact 0
		.amdhsa_exception_int_div_zero 0
	.end_amdhsa_kernel

amdhsa.kernels:
  - .agpr_count:     0
    .args:
      - .offset:         0
        .size:           280
        .value_kind:     by_value
      - .offset:         280
        .size:           4
        .value_kind:     hidden_block_count_x
      - .offset:         284
        .size:           4
        .value_kind:     hidden_block_count_y
      - .offset:         288
        .size:           4
        .value_kind:     hidden_block_count_z
      - .offset:         292
        .size:           2
        .value_kind:     hidden_group_size_x
      - .offset:         294
        .size:           2
        .value_kind:     hidden_group_size_y
      - .offset:         296
        .size:           2
        .value_kind:     hidden_group_size_z
      - .offset:         298
        .size:           2
        .value_kind:     hidden_remainder_x
      - .offset:         300
        .size:           2
        .value_kind:     hidden_remainder_y
      - .offset:         302
        .size:           2
        .value_kind:     hidden_remainder_z
      - .offset:         320
        .size:           8
        .value_kind:     hidden_global_offset_x
      - .offset:         328
        .size:           8
        .value_kind:     hidden_global_offset_y
      - .offset:         336
        .size:           8
        .value_kind:     hidden_global_offset_z
      - .offset:         344
        .size:           2
        .value_kind:     hidden_grid_dims
      - .offset:         368
        .size:           8
        .value_kind:     hidden_multigrid_sync_arg
      - .offset:         400
        .size:           4
        .value_kind:     hidden_dynamic_lds_size
    .group_segment_fixed_size: 0
    .kernarg_segment_align: 8
    .kernarg_segment_size: 536
    .language:       OpenCL C
    .language_version:
      - 2
      - 0
    .max_flat_workgroup_size: 512
    .name:           _Z10fwd_kernel2Pm
    .private_segment_fixed_size: 0
    .sgpr_count:     108
    .sgpr_spill_count: 2
    .symbol:         _Z10fwd_kernel2Pm.kd
    .uniform_work_group_size: 1
    .uses_dynamic_stack: false
    .vgpr_count:     256
    .vgpr_spill_count: 0
    .wavefront_size: 64
